# A and B/D attention loops: no per-segment s_setprio toggles; waves 4-7 run the loops at static priority 1
# speedup vs baseline: 1.0002x; 1.0002x over previous
; __device__ __forceinline__ unsigned pk2(float lo, float hi) { unsigned r; asm volatile("v_cvt_pk_bf16_f32 %0, %1, %2" : "=v"(r) : "v"(lo), "v"(hi)); return r; }
; __device__ __forceinline__ float silu_f(float z) { return z * __builtin_amdgcn_rcpf(1.0f + fexp2(-LOG2E * z)); }
; template <int DQK, int MODE>
; __device__ __forceinline__ void attn_unit(LAS unsigned char* lds, const AttnArgs& a, const unsigned char* lut) {
;     ...
; #pragma unroll
;     for (int qt = 0; qt < 2; ++qt) {
;         const int qr = qi + qt * 16;
;         float lt = lsum[qt]; lt += __shfl_xor(lt, 16); lt += __shfl_xor(lt, 32);
;         const float inv = 1.0f / lt;
;         u32x2 zw[4];
; #pragma unroll
;         for (int dt = 0; dt < 4; ++dt) zw[dt] = (u32x2){0x3f803f80u, 0x3f803f80u};
;         if (a.z) {
; #pragma unroll
;             for (int dt = 0; dt < 4; ++dt) zw[dt] = *(const u32x2*)(a.z + (long)qr * a.z_rs + dt * 16 + lg * 4);
;         }
; #pragma unroll
;         for (int dt = 0; dt < 4; ++dt) {
;             float r[4];
; #pragma unroll
;             for (int j = 0; j < 4; ++j) r[j] = o[qt][dt][j] * inv;
;             const int col = dt * 16 + lg * 4;
;             if (a.z) {
;                 r[0] *= silu_f(__uint_as_float(zw[dt].x << 16)); r[1] *= silu_f(__uint_as_float(zw[dt].x & 0xffff0000u));
;                 r[2] *= silu_f(__uint_as_float(zw[dt].y << 16)); r[3] *= silu_f(__uint_as_float(zw[dt].y & 0xffff0000u)); }
;             u32x2 w; w.x = pk2(r[0], r[1]); w.y = pk2(r[2], r[3]);
;             *(u32x2*)(a.o + (long)qr * a.o_rs + col) = w;
;         }
;     ...
;     }
.LBB0_310:
	s_setprio 0
	v_cmp_lt_i32_e32 vcc, v204, v199
	s_lshl_b64 s[0:1], s[38:39], 25
	v_readlane_b32 s12, v253, 1
	v_cndmask_b32_e32 v0, v197, v204, vcc
	v_cmp_lt_i32_e32 vcc, v205, v199
	v_lshlrev_b32_e32 v36, 2, v0
	s_add_u32 s0, s12, s0
	v_cndmask_b32_e32 v0, v197, v205, vcc
	v_lshlrev_b32_e32 v37, 2, v0
	ds_bpermute_b32 v0, v36, v95
	v_readlane_b32 s12, v253, 2
	s_addc_u32 s1, s12, s1
	s_add_u32 s0, s0, s40
	s_addc_u32 s1, s1, s41
	s_waitcnt lgkmcnt(0)
	v_add_f32_e32 v0, v95, v0
	ds_bpermute_b32 v26, v37, v0
	s_waitcnt lgkmcnt(0)
	v_add_f32_e32 v0, v0, v26
	v_div_scale_f32 v26, s[12:13], v0, v0, 1.0
	v_rcp_f32_e32 v27, v26
	s_nop 0
	v_fma_f32 v28, -v26, v27, 1.0
	v_fmac_f32_e32 v27, v28, v27
	v_div_scale_f32 v28, vcc, 1.0, v0, 1.0
	v_mul_f32_e32 v29, v28, v27
	v_fma_f32 v30, -v26, v29, v28
	v_fmac_f32_e32 v29, v30, v27
	v_fma_f32 v26, -v26, v29, v28
	v_div_fmas_f32 v26, v26, v27, v29
	v_div_fixup_f32 v26, v26, v0, 1.0
	v_lshl_add_u64 v[28:29], v[120:121], 1, s[30:31]
	v_lshlrev_b32_e32 v0, 1, v54
	v_lshl_add_u64 v[28:29], v[28:29], 0, v[0:1]
	global_load_dwordx2 v[30:31], v[28:29], off offset:3072
	global_load_dwordx2 v[34:35], v[28:29], off offset:3104
	global_load_dwordx2 v[32:33], v[28:29], off offset:3136
	s_nop 0
	global_load_dwordx2 v[28:29], v[28:29], off offset:3168
	s_waitcnt vmcnt(3)
	v_lshlrev_b32_e32 v27, 16, v30
	v_mul_f32_e32 v38, 0xbfb8aa3b, v27
	v_exp_f32_e32 v38, v38
	s_nop 0
	v_add_f32_e32 v38, 1.0, v38
	v_rcp_f32_e32 v39, v38
	v_mov_b32_e32 v38, v50
	v_pk_mul_f32 v[38:39], v[38:39], v[26:27]
	v_and_b32_e32 v27, 0xffff0000, v30
	v_mul_f32_e32 v30, 0xbfb8aa3b, v27
	v_exp_f32_e32 v30, v30
	v_mul_f32_e32 v40, v38, v39
	v_mov_b32_e32 v38, v51
	v_add_f32_e32 v30, 1.0, v30
	v_rcp_f32_e32 v39, v30
	s_nop 0
	v_pk_mul_f32 v[38:39], v[38:39], v[26:27]
	v_lshlrev_b32_e32 v27, 16, v31
	v_mul_f32_e32 v30, 0xbfb8aa3b, v27
	v_exp_f32_e32 v30, v30
	v_mul_f32_e32 v41, v38, v39
	v_mov_b32_e32 v38, v52
	v_add_f32_e32 v30, 1.0, v30
	v_rcp_f32_e32 v39, v30
	s_nop 0
	v_pk_mul_f32 v[38:39], v[38:39], v[26:27]
	v_and_b32_e32 v27, 0xffff0000, v31
	v_mul_f32_e32 v30, 0xbfb8aa3b, v27
	v_exp_f32_e32 v30, v30
	v_mul_f32_e32 v39, v38, v39
	v_cvt_pk_bf16_f32 v38, v40, v41
	v_add_f32_e32 v30, 1.0, v30
	v_rcp_f32_e32 v31, v30
	v_mov_b32_e32 v30, v53
	v_pk_mul_f32 v[30:31], v[30:31], v[26:27]
	s_nop 0
	v_mul_f32_e32 v27, v30, v31
	v_lshlrev_b64 v[30:31], 12, v[118:119]
	v_lshl_add_u64 v[30:31], s[0:1], 0, v[30:31]
	v_cvt_pk_bf16_f32 v39, v39, v27
	v_lshl_add_u64 v[30:31], v[30:31], 0, v[0:1]
	s_waitcnt vmcnt(2)
	v_lshlrev_b32_e32 v27, 16, v34
	global_store_dwordx2 v[30:31], v[38:39], off
	v_mul_f32_e32 v38, 0xbfb8aa3b, v27
	v_exp_f32_e32 v38, v38
	s_nop 0
	v_add_f32_e32 v38, 1.0, v38
	v_rcp_f32_e32 v39, v38
	v_mov_b32_e32 v38, v42
	v_pk_mul_f32 v[38:39], v[38:39], v[26:27]
	v_and_b32_e32 v27, 0xffff0000, v34
	v_mul_f32_e32 v34, 0xbfb8aa3b, v27
	v_exp_f32_e32 v34, v34
	v_mul_f32_e32 v40, v38, v39
	v_mov_b32_e32 v38, v43
	v_add_f32_e32 v34, 1.0, v34
	v_rcp_f32_e32 v39, v34
	s_nop 0
	v_pk_mul_f32 v[38:39], v[38:39], v[26:27]
	v_lshlrev_b32_e32 v27, 16, v35
	v_mul_f32_e32 v34, 0xbfb8aa3b, v27
	v_exp_f32_e32 v34, v34
	v_mul_f32_e32 v41, v38, v39
	v_mov_b32_e32 v38, v44
	v_add_f32_e32 v34, 1.0, v34
	v_rcp_f32_e32 v39, v34
	s_nop 0
	v_pk_mul_f32 v[38:39], v[38:39], v[26:27]
	v_and_b32_e32 v27, 0xffff0000, v35
	v_mul_f32_e32 v34, 0xbfb8aa3b, v27
	v_exp_f32_e32 v34, v34
	v_mul_f32_e32 v38, v38, v39
	v_add_f32_e32 v34, 1.0, v34
	v_rcp_f32_e32 v35, v34
	v_mov_b32_e32 v34, v45
	v_pk_mul_f32 v[34:35], v[34:35], v[26:27]
	s_nop 0
	v_mul_f32_e32 v27, v34, v35
	v_cvt_pk_bf16_f32 v34, v40, v41
	v_cvt_pk_bf16_f32 v35, v38, v27
	s_waitcnt vmcnt(2)
	v_lshlrev_b32_e32 v27, 16, v32
	global_store_dwordx2 v[30:31], v[34:35], off offset:32
	v_mul_f32_e32 v34, 0xbfb8aa3b, v27
	v_exp_f32_e32 v34, v34
	s_nop 0
	v_add_f32_e32 v34, 1.0, v34
	v_rcp_f32_e32 v35, v34
	v_mov_b32_e32 v34, v22
	v_pk_mul_f32 v[34:35], v[34:35], v[26:27]
	v_and_b32_e32 v27, 0xffff0000, v32
	v_mul_f32_e32 v22, 0xbfb8aa3b, v27
	v_exp_f32_e32 v22, v22
	v_mul_f32_e32 v38, v34, v35
	v_mov_b32_e32 v34, v23
	v_add_f32_e32 v22, 1.0, v22
	v_rcp_f32_e32 v35, v22
	s_nop 0
	v_pk_mul_f32 v[22:23], v[34:35], v[26:27]
	v_lshlrev_b32_e32 v27, 16, v33
	v_mul_f32_e32 v32, v22, v23
	v_mul_f32_e32 v22, 0xbfb8aa3b, v27
	v_exp_f32_e32 v22, v22
	s_nop 0
	v_add_f32_e32 v22, 1.0, v22
	v_rcp_f32_e32 v23, v22
	v_mov_b32_e32 v22, v24
	v_pk_mul_f32 v[22:23], v[22:23], v[26:27]
	v_and_b32_e32 v27, 0xffff0000, v33
	v_mul_f32_e32 v24, v22, v23
	v_mul_f32_e32 v22, 0xbfb8aa3b, v27
	v_exp_f32_e32 v22, v22
	s_nop 0
	v_add_f32_e32 v22, 1.0, v22
	v_rcp_f32_e32 v23, v22
	v_mov_b32_e32 v22, v25
	v_pk_mul_f32 v[22:23], v[22:23], v[26:27]
	s_nop 0
	v_mul_f32_e32 v23, v22, v23
	v_cvt_pk_bf16_f32 v22, v38, v32
	s_waitcnt vmcnt(2)
	v_lshlrev_b32_e32 v27, 16, v28
	v_cvt_pk_bf16_f32 v23, v24, v23
	global_store_dwordx2 v[30:31], v[22:23], off offset:64
	v_mul_f32_e32 v22, 0xbfb8aa3b, v27
	v_exp_f32_e32 v22, v22
	s_nop 0
	v_add_f32_e32 v22, 1.0, v22
	v_rcp_f32_e32 v23, v22
	v_mov_b32_e32 v22, v18
	v_pk_mul_f32 v[22:23], v[22:23], v[26:27]
	v_and_b32_e32 v27, 0xffff0000, v28
	v_mul_f32_e32 v18, 0xbfb8aa3b, v27
	v_exp_f32_e32 v18, v18
	v_mul_f32_e32 v24, v22, v23
	v_mov_b32_e32 v22, v19
	v_add_f32_e32 v18, 1.0, v18
	v_rcp_f32_e32 v23, v18
	s_nop 0
	v_pk_mul_f32 v[18:19], v[22:23], v[26:27]
	v_lshlrev_b32_e32 v27, 16, v29
	v_mul_f32_e32 v22, v18, v19
	v_mul_f32_e32 v18, 0xbfb8aa3b, v27
	v_exp_f32_e32 v18, v18
	s_nop 0
	v_add_f32_e32 v18, 1.0, v18
	v_rcp_f32_e32 v19, v18
	v_mov_b32_e32 v18, v20
	v_pk_mul_f32 v[18:19], v[18:19], v[26:27]
	v_and_b32_e32 v27, 0xffff0000, v29
	v_mul_f32_e32 v20, v18, v19
	v_mul_f32_e32 v18, 0xbfb8aa3b, v27
	v_exp_f32_e32 v18, v18
	s_nop 0
	v_add_f32_e32 v18, 1.0, v18
	v_rcp_f32_e32 v19, v18
	v_mov_b32_e32 v18, v21
	v_pk_mul_f32 v[18:19], v[18:19], v[26:27]
	s_nop 0
	v_mul_f32_e32 v19, v18, v19
	v_cvt_pk_bf16_f32 v18, v24, v22
	v_cvt_pk_bf16_f32 v19, v20, v19
	global_store_dwordx2 v[30:31], v[18:19], off offset:96
	ds_bpermute_b32 v18, v36, v94
	s_waitcnt lgkmcnt(0)
; __device__ __forceinline__ unsigned pk2(float lo, float hi) { unsigned r; asm volatile("v_cvt_pk_bf16_f32 %0, %1, %2" : "=v"(r) : "v"(lo), "v"(hi)); return r; }
; __device__ __forceinline__ float silu_f(float z) { return z * __builtin_amdgcn_rcpf(1.0f + fexp2(-LOG2E * z)); }
; template <int DQK, int MODE>
; __device__ __forceinline__ void attn_unit(LAS unsigned char* lds, const AttnArgs& a, const unsigned char* lut) {
;     ...
; #pragma unroll
;     for (int qt = 0; qt < 2; ++qt) {
;         const int qr = qi + qt * 16;
;         float lt = lsum[qt]; lt += __shfl_xor(lt, 16); lt += __shfl_xor(lt, 32);
;         const float inv = 1.0f / lt;
;         u32x2 zw[4];
; #pragma unroll
;         for (int dt = 0; dt < 4; ++dt) zw[dt] = (u32x2){0x3f803f80u, 0x3f803f80u};
;         if (a.z) {
; #pragma unroll
;             for (int dt = 0; dt < 4; ++dt) zw[dt] = *(const u32x2*)(a.z + (long)qr * a.z_rs + dt * 16 + lg * 4);
;         }
; #pragma unroll
;         for (int dt = 0; dt < 4; ++dt) {
;             float r[4];
; #pragma unroll
;             for (int j = 0; j < 4; ++j) r[j] = o[qt][dt][j] * inv;
;             const int col = dt * 16 + lg * 4;
;             if (a.z) {
;                 r[0] *= silu_f(__uint_as_float(zw[dt].x << 16)); r[1] *= silu_f(__uint_as_float(zw[dt].x & 0xffff0000u));
;                 r[2] *= silu_f(__uint_as_float(zw[dt].y << 16)); r[3] *= silu_f(__uint_as_float(zw[dt].y & 0xffff0000u)); }
;             u32x2 w; w.x = pk2(r[0], r[1]); w.y = pk2(r[2], r[3]);
;             *(u32x2*)(a.o + (long)qr * a.o_rs + col) = w;
;         }
;     ...
;     }
	v_add_f32_e32 v18, v94, v18
	ds_bpermute_b32 v19, v37, v18
	s_waitcnt lgkmcnt(0)
	v_add_f32_e32 v18, v18, v19
	v_div_scale_f32 v19, s[12:13], v18, v18, 1.0
	v_rcp_f32_e32 v20, v19
	s_nop 0
	v_fma_f32 v21, -v19, v20, 1.0
	v_fmac_f32_e32 v20, v21, v20
	v_div_scale_f32 v21, vcc, 1.0, v18, 1.0
	v_mul_f32_e32 v22, v21, v20
	v_fma_f32 v23, -v19, v22, v21
	v_fmac_f32_e32 v22, v23, v20
	v_fma_f32 v19, -v19, v22, v21
	v_div_fmas_f32 v19, v19, v20, v22
	v_lshl_add_u64 v[20:21], v[116:117], 1, s[30:31]
	v_lshl_add_u64 v[20:21], v[20:21], 0, v[0:1]
	global_load_dwordx2 v[26:27], v[20:21], off offset:3072
	global_load_dwordx2 v[24:25], v[20:21], off offset:3104
	global_load_dwordx2 v[22:23], v[20:21], off offset:3136
	s_nop 0
	global_load_dwordx2 v[20:21], v[20:21], off offset:3168
	v_div_fixup_f32 v18, v19, v18, 1.0
	s_waitcnt vmcnt(3)
	v_lshlrev_b32_e32 v19, 16, v26
	v_mul_f32_e32 v28, 0xbfb8aa3b, v19
	v_exp_f32_e32 v28, v28
	s_nop 0
	v_add_f32_e32 v28, 1.0, v28
	v_rcp_f32_e32 v29, v28
	v_mov_b32_e32 v28, v14
	v_pk_mul_f32 v[28:29], v[28:29], v[18:19]
	v_and_b32_e32 v19, 0xffff0000, v26
	v_mul_f32_e32 v14, 0xbfb8aa3b, v19
	v_exp_f32_e32 v14, v14
	v_mul_f32_e32 v30, v28, v29
	v_mov_b32_e32 v28, v15
	v_add_f32_e32 v14, 1.0, v14
	v_rcp_f32_e32 v29, v14
	s_nop 0
	v_pk_mul_f32 v[14:15], v[28:29], v[18:19]
	v_lshlrev_b32_e32 v19, 16, v27
	v_mul_f32_e32 v26, v14, v15
	v_mul_f32_e32 v14, 0xbfb8aa3b, v19
	v_exp_f32_e32 v14, v14
	s_nop 0
	v_add_f32_e32 v14, 1.0, v14
	v_rcp_f32_e32 v15, v14
	v_mov_b32_e32 v14, v16
	v_cvt_pk_bf16_f32 v16, v30, v26
	v_pk_mul_f32 v[14:15], v[14:15], v[18:19]
	v_and_b32_e32 v19, 0xffff0000, v27
	v_mul_f32_e32 v28, v14, v15
	v_mul_f32_e32 v14, 0xbfb8aa3b, v19
	v_exp_f32_e32 v14, v14
	s_nop 0
	v_add_f32_e32 v14, 1.0, v14
	v_rcp_f32_e32 v15, v14
	v_mov_b32_e32 v14, v17
	v_pk_mul_f32 v[14:15], v[14:15], v[18:19]
	s_nop 0
	v_mul_f32_e32 v14, v14, v15
	v_cvt_pk_bf16_f32 v17, v28, v14
	v_lshlrev_b64 v[14:15], 12, v[114:115]
	v_lshl_add_u64 v[14:15], s[0:1], 0, v[14:15]
	s_waitcnt vmcnt(2)
	v_lshlrev_b32_e32 v19, 16, v24
	v_lshl_add_u64 v[14:15], v[14:15], 0, v[0:1]
	v_mul_f32_e32 v0, 0xbfb8aa3b, v19
	v_exp_f32_e32 v0, v0
	global_store_dwordx2 v[14:15], v[16:17], off
	v_mov_b32_e32 v16, v10
	s_mov_b64 s[0:1], 0
	v_add_f32_e32 v0, 1.0, v0
	v_rcp_f32_e32 v17, v0
	s_nop 0
	v_pk_mul_f32 v[16:17], v[16:17], v[18:19]
	v_and_b32_e32 v19, 0xffff0000, v24
	v_mul_f32_e32 v10, 0xbfb8aa3b, v19
	v_exp_f32_e32 v10, v10
	v_mul_f32_e32 v0, v16, v17
	v_mov_b32_e32 v16, v11
	v_add_f32_e32 v10, 1.0, v10
	v_rcp_f32_e32 v17, v10
	s_nop 0
	v_pk_mul_f32 v[10:11], v[16:17], v[18:19]
	v_lshlrev_b32_e32 v19, 16, v25
	v_mul_f32_e32 v16, v10, v11
	v_mul_f32_e32 v10, 0xbfb8aa3b, v19
	v_exp_f32_e32 v10, v10
	s_nop 0
	v_add_f32_e32 v10, 1.0, v10
	v_rcp_f32_e32 v11, v10
	v_mov_b32_e32 v10, v12
	v_pk_mul_f32 v[10:11], v[10:11], v[18:19]
	v_and_b32_e32 v19, 0xffff0000, v25
	v_mul_f32_e32 v12, v10, v11
	v_mul_f32_e32 v10, 0xbfb8aa3b, v19
	v_exp_f32_e32 v10, v10
	s_nop 0
	v_add_f32_e32 v10, 1.0, v10
	v_rcp_f32_e32 v11, v10
	v_mov_b32_e32 v10, v13
	v_pk_mul_f32 v[10:11], v[10:11], v[18:19]
	s_waitcnt vmcnt(2)
	v_lshlrev_b32_e32 v19, 16, v22
	v_mul_f32_e32 v11, v10, v11
	v_cvt_pk_bf16_f32 v10, v0, v16
	v_mul_f32_e32 v0, 0xbfb8aa3b, v19
	v_exp_f32_e32 v0, v0
	v_cvt_pk_bf16_f32 v11, v12, v11
	global_store_dwordx2 v[14:15], v[10:11], off offset:32
	v_mov_b32_e32 v10, v6
	v_add_f32_e32 v0, 1.0, v0
	v_rcp_f32_e32 v11, v0
	s_nop 0
	v_pk_mul_f32 v[10:11], v[10:11], v[18:19]
	v_and_b32_e32 v19, 0xffff0000, v22
	v_mul_f32_e32 v6, 0xbfb8aa3b, v19
	v_exp_f32_e32 v6, v6
	v_mul_f32_e32 v0, v10, v11
	v_mov_b32_e32 v10, v7
	v_add_f32_e32 v6, 1.0, v6
	v_rcp_f32_e32 v11, v6
	s_nop 0
	v_pk_mul_f32 v[6:7], v[10:11], v[18:19]
	v_lshlrev_b32_e32 v19, 16, v23
	v_mul_f32_e32 v10, v6, v7
	v_mul_f32_e32 v6, 0xbfb8aa3b, v19
	v_exp_f32_e32 v6, v6
	s_nop 0
	v_add_f32_e32 v6, 1.0, v6
	v_rcp_f32_e32 v7, v6
	v_mov_b32_e32 v6, v8
	v_pk_mul_f32 v[6:7], v[6:7], v[18:19]
	v_and_b32_e32 v19, 0xffff0000, v23
	v_mul_f32_e32 v8, v6, v7
	v_mul_f32_e32 v6, 0xbfb8aa3b, v19
	v_exp_f32_e32 v6, v6
	s_nop 0
	v_add_f32_e32 v6, 1.0, v6
	v_rcp_f32_e32 v7, v6
	v_mov_b32_e32 v6, v9
	v_pk_mul_f32 v[6:7], v[6:7], v[18:19]
	s_waitcnt vmcnt(2)
	v_lshlrev_b32_e32 v19, 16, v20
	v_mul_f32_e32 v7, v6, v7
	v_cvt_pk_bf16_f32 v6, v0, v10
	v_mul_f32_e32 v0, 0xbfb8aa3b, v19
	v_exp_f32_e32 v0, v0
	v_cvt_pk_bf16_f32 v7, v8, v7
	global_store_dwordx2 v[14:15], v[6:7], off offset:64
	v_mov_b32_e32 v6, v2
	v_add_f32_e32 v0, 1.0, v0
	v_rcp_f32_e32 v7, v0
	s_nop 0
	v_pk_mul_f32 v[6:7], v[6:7], v[18:19]
	v_and_b32_e32 v19, 0xffff0000, v20
	v_mul_f32_e32 v2, 0xbfb8aa3b, v19
	v_exp_f32_e32 v2, v2
	v_mul_f32_e32 v0, v6, v7
	v_mov_b32_e32 v6, v3
	v_add_f32_e32 v2, 1.0, v2
	v_rcp_f32_e32 v7, v2
	s_nop 0
	v_pk_mul_f32 v[2:3], v[6:7], v[18:19]
	v_lshlrev_b32_e32 v19, 16, v21
	v_mul_f32_e32 v6, v2, v3
	v_mul_f32_e32 v2, 0xbfb8aa3b, v19
	v_exp_f32_e32 v2, v2
	s_nop 0
	v_add_f32_e32 v2, 1.0, v2
	v_rcp_f32_e32 v3, v2
	v_mov_b32_e32 v2, v4
	v_pk_mul_f32 v[2:3], v[2:3], v[18:19]
	v_and_b32_e32 v19, 0xffff0000, v21
	v_mul_f32_e32 v4, v2, v3
	v_mul_f32_e32 v2, 0xbfb8aa3b, v19
	v_exp_f32_e32 v2, v2
	s_nop 0
	v_add_f32_e32 v2, 1.0, v2
	v_rcp_f32_e32 v3, v2
	v_mov_b32_e32 v2, v5
	v_pk_mul_f32 v[2:3], v[2:3], v[18:19]
	s_nop 0
	v_mul_f32_e32 v3, v2, v3
	v_cvt_pk_bf16_f32 v2, v0, v6
	v_cvt_pk_bf16_f32 v3, v4, v3
	global_store_dwordx2 v[14:15], v[2:3], off offset:96

; #define ATT_LOAD(kt) do { const long kb_ = (long)(kt) * 64; \
;         rk0 = *(const u32x4*)(a.k + (kb_ + kkey0) * a.k_rs + kpart0 * 8); \
;         if (DQK == 96 && tid < 256) rk1 = *(const u32x4*)(a.k + (kb_ + kkey1) * a.k_rs + kpart1 * 8); \
;         rv0 = *(const u32x2*)(a.v + (kb_ + 2 * vkp) * a.v_rs + vdg * 4); rv1 = *(const u32x2*)(a.v + (kb_ + 2 * vkp + 1) * a.v_rs + vdg * 4); } while (0)
; template <int DQK, int MODE>
; __device__ __forceinline__ void attn_unit(LAS unsigned char* lds, const AttnArgs& a, const unsigned char* lut) {
;     ...
;     float lsum[2]; lsum[0] = (lg == 0) ? a.l_init : 0.f; lsum[1] = lsum[0];
;     const float nb = -a.bound;
;     f32x4 o[2][4];
; #pragma unroll
;     for (int qt = 0; qt < 2; ++qt)
; #pragma unroll
;         for (int d = 0; d < 4; ++d) o[qt][d] = (f32x4){0.f, 0.f, 0.f, 0.f};
;     u32x4 rk0, rk1; u32x2 rv0, rv1;
;     const int kkey0 = tid / KCH, kpart0 = tid % KCH; const int kkey1 = (tid + 512) / KCH, kpart1 = (tid + 512) % KCH;
;     const int vkp = tid & 31, vdg = tid >> 5;
;     ...
;     ATT_LOAD(kt_lo);
;     ATT_STORE(0);
;     if (kt_lo < kt_hi) ATT_LOAD(kt_lo + 1);
;     unsigned long long mwn0 = 0ull, mwn1 = 0ull;
;     if (MODE == 2) { mwn0 = a.mask[(long)qi * 128 + kt_lo]; mwn1 = a.mask[(long)(qi + 16) * 128 + kt_lo]; }
;     __syncthreads();
.LBB0_329:
	s_ashr_i32 s39, s38, 31
	s_lshl_b64 s[0:1], s[38:39], 23
	v_ashrrev_i32_e32 v119, 31, v118
	s_add_u32 s20, s72, s0
	v_ashrrev_i32_e32 v115, 31, v114
	s_addc_u32 s21, s73, s1
	v_lshlrev_b64 v[4:5], 10, v[118:119]
	v_lshl_add_u64 v[12:13], s[20:21], 0, v[4:5]
	v_lshlrev_b64 v[6:7], 10, v[114:115]
	v_lshl_add_u64 v[14:15], s[20:21], 0, v[6:7]
	global_load_dwordx2 v[62:63], v[12:13], off
	global_load_dwordx2 v[64:65], v[14:15], off
	s_cmp_lt_i32 s12, 0
	v_lshlrev_b32_e32 v54, 2, v10
	s_waitcnt lgkmcnt(0)
	s_barrier
	s_cbranch_scc1 .LBB0_309
	s_or_b32 s13, s13, 31
	v_readlane_b32 s19, v254, 0
	s_add_u32 s0, s19, s0
	v_readlane_b32 s19, v254, 1
	s_addc_u32 s1, s19, s1
	v_lshl_add_u64 v[128:129], s[0:1], 0, v[6:7]
	v_lshl_add_u64 v[130:131], s[0:1], 0, v[4:5]
	s_add_u32 s0, s18, s40
	s_addc_u32 s1, s14, s41
	v_and_b32_e32 v6, 31, v8
	v_mov_b64_e32 v[4:5], s[0:1]
	s_mov_b32 s14, 0x9800
	s_add_u32 s0, s0, 0xcb2a500
	v_lshlrev_b32_e32 v159, 3, v10
	v_mad_i64_i32 v[10:11], s[20:21], v11, s4, 0
	v_mad_u64_u32 v[4:5], s[18:19], v6, s14, v[4:5]
	s_addc_u32 s1, s1, 0
	v_lshl_add_u64 v[132:133], v[2:3], 1, v[4:5]
	v_lshl_add_u64 v[2:3], s[0:1], 0, v[10:11]
	s_lshl_b32 s0, s15, 10
	s_lshl_b32 s1, s17, 7
	s_add_i32 s0, s0, s1
	v_lshl_add_u64 v[134:135], v[122:123], 1, v[2:3]
	v_lshl_or_b32 v2, v9, 2, s0
	s_lshl_b32 s16, s16, 10
	v_sub_u32_e32 v2, v2, v0
	v_mov_b32_e32 v4, v1
	v_mov_b32_e32 v5, v1
	s_mul_i32 s20, s17, 0x84
	v_mul_u32_u24_e32 v160, 0x90, v9
	v_xor_b32_e32 v56, 0x80000000, v55
	s_sub_i32 s1, s0, s16
	v_subrev_u32_e32 v123, s16, v2
	v_mov_b32_e32 v2, v1
	v_mov_b32_e32 v3, v1
	v_mov_b32_e32 v94, 0
	v_mov_b64_e32 v[8:9], v[4:5]
	v_mov_b64_e32 v[12:13], v[4:5]
	v_mov_b64_e32 v[16:17], v[4:5]
	v_mov_b64_e32 v[20:21], v[4:5]
	v_mov_b64_e32 v[24:25], v[4:5]
	v_mov_b64_e32 v[44:45], v[4:5]
	v_mov_b64_e32 v[52:53], v[4:5]
	v_mov_b32_e32 v57, v56
	v_mov_b32_e32 v58, v56
	v_mov_b32_e32 v59, v56
	v_mov_b32_e32 v60, v54
	s_add_i32 s14, s20, 0x14800
	s_add_i32 s15, s1, 0x13d80
	s_lshl_b32 s0, s17, 8
	s_add_i32 s0, s0, 0x16000
	v_mbcnt_lo_u32_b32 v161, -1, 0
	v_mbcnt_hi_u32_b32 v161, -1, v161
	v_mov_b32_e32 v162, s0
	v_lshl_add_u32 v163, v161, 2, v162
	v_mov_b32_e32 v164, 0xf149f2ca
	v_readfirstlane_b32 s0, v192
	s_bitcmp1_b32 s0, 8
	s_cbranch_scc0 .Lmy_prio_a
	s_setprio 1
.Lmy_prio_a:
	v_mov_b32_e32 v165, s14
	v_mov_b32_e32 v161, s15
	ds_read_u8 v97, v165
	ds_read_b32 v217, v161
	s_waitcnt lgkmcnt(0)
	s_mov_b32 s16, 0
	v_mov_b32_e32 v136, v1
	v_mov_b32_e32 v137, v1
	v_mov_b64_e32 v[6:7], v[2:3]
	v_mov_b64_e32 v[10:11], v[2:3]
	v_mov_b64_e32 v[14:15], v[2:3]
	v_mov_b64_e32 v[18:19], v[2:3]
	v_mov_b64_e32 v[22:23], v[2:3]
	v_mov_b64_e32 v[42:43], v[2:3]
	v_mov_b64_e32 v[50:51], v[2:3]
	s_mov_b32 s17, 0
	v_mov_b32_e32 v95, v94

; template <int DQK, int VAR> ...
;     ...
;         for (int c = 0; c < 2; ++c) {
;             s[0][ch * 2 + c] = (f32x4){sinit, sinit, sinit, sinit}; s[1][ch * 2 + c] = s[0][ch * 2 + c];
; #pragma unroll
;             for (int ks = 0; ks < DQK / 32; ++ks) {
;                 s[0][ch * 2 + c] = __builtin_amdgcn_mfma_f32_16x16x32_bf16(kfr[c][ks], qf[0][ks], s[0][ch * 2 + c], 0, 0, 0);
;                 s[1][ch * 2 + c] = __builtin_amdgcn_mfma_f32_16x16x32_bf16(kfr[c][ks], qf[1][ks], s[1][ch * 2 + c], 0, 0, 0);
;             }
;         }
;         __builtin_amdgcn_s_setprio(0);
;         __builtin_amdgcn_sched_barrier(0);
;     }
;     __builtin_amdgcn_s_setprio(0);
;     __builtin_amdgcn_sched_barrier(0);
; #pragma unroll
;     for (int kk = 0; kk < 2; ++kk)
; #pragma unroll
;         for (int dt = 0; dt < 4; ++dt) {
;             const LAS bf16_t* vp = sVt + (dt * 16 + lr) * VP + kk * 32 + lg * 4;
;             const u32x2 v0 = *(const LAS u32x2*)vp, v1 = *(const LAS u32x2*)(vp + 16);
;             vfr[kk][dt].x = v0.x; vfr[kk][dt].y = v0.y; vfr[kk][dt].z = v1.x; vfr[kk][dt].w = v1.y;
;         }
;     __builtin_amdgcn_sched_barrier(0);
; #pragma unroll
;     for (int qt = 0; qt < 2; ++qt) {
;         const int dq = qi + qt * 16 - key0 - lg * 4;
;         const LAS float* bp = sBias + (dq + 33);
;         float ps = 0.f;
; #pragma unroll
;         for (int c = 0; c < 4; ++c)
; #pragma unroll
;             for (int j = 0; j < 4; ++j) {
;                 float val = s[qt][c][j]; float pv;
;                 if (VAR == 0) pv = fexp2(val);
;                 else if (VAR == 1) { pv = fexp2(val); pv = (dq >= c * 16 + j) ? pv : 0.f; }
;                 else if (VAR == 2) { pv = fexp2(val + bp[63 - (c * 16 + j)]); }
;                 else if (VAR == 3) { pv = fexp2(val); pv = __uint_as_float(__float_as_uint(pv) & (unsigned)__builtin_amdgcn_sbfe((int)(c < 2 ? mlo[qt] : mhi[qt]), (c & 1) * 16 + j, 1)); }
;                 else { pv = fexp2(val + bp[63 - (c * 16 + j)]); pv = __uint_as_float(__float_as_uint(pv) & (unsigned)__builtin_amdgcn_sbfe((int)(c < 2 ? mlo[qt] : mhi[qt]), (c & 1) * 16 + j, 1)); }
;                 s[qt][c][j] = pv; ps += pv;
;             }
;         lsum[qt] += ps;
;     }
;     __builtin_amdgcn_s_setprio(1);
; #pragma unroll
;     for (int kk = 0; kk < 2; ++kk) {
;         bf16x8 pb[2];
; #pragma unroll
;         for (int qt = 0; qt < 2; ++qt) {
.LBB0_338:
	s_mulk_i32 s19, 0x6000
	v_lshrrev_b64 v[62:63], v60, v[62:63]
	v_lshrrev_b64 v[64:65], v54, v[64:65]
	s_add_i32 s0, s19, 0
	v_add3_u32 v96, s0, v0, v160
	s_movk_i32 s0, 0xf0
	v_lshlrev_b32_e32 v69, 4, v62
	v_lshrrev_b32_e32 v70, 12, v62
	v_lshlrev_b32_e32 v71, 4, v63
	v_lshrrev_b32_e32 v72, 12, v63
	v_lshlrev_b32_e32 v73, 4, v64
	v_lshrrev_b32_e32 v74, 12, v64
	v_lshlrev_b32_e32 v75, 4, v65
	v_lshrrev_b32_e32 v76, 12, v65
	v_and_or_b32 v69, v69, s0, v162
	v_and_or_b32 v70, v70, s0, v162
	v_and_or_b32 v71, v71, s0, v162
	v_and_or_b32 v72, v72, s0, v162
	v_and_or_b32 v73, v73, s0, v162
	v_and_or_b32 v74, v74, s0, v162
	v_and_or_b32 v75, v75, s0, v162
	v_and_or_b32 v76, v76, s0, v162
	s_mov_b32 vcc_lo, 0x76543210
	s_mov_b32 vcc_hi, 0xfedcba98
	v_readfirstlane_b32 s1, v97
	v_sub_f32_e32 v78, v217, v55
	s_nop 0
	s_cmp_lg_u32 s1, 0
	s_cselect_b64 s[36:37], -1, 0
	v_cndmask_b32_e64 v77, v56, v78, s[36:37]
	v_cndmask_b32_e32 v77, v164, v77, vcc
	ds_write_b32 v163, v77
	ds_read_b128 v[80:83], v69
	ds_read_b128 v[84:87], v73
	ds_read_b128 v[148:151], v96
	ds_read_b128 v[152:155], v96 offset:64
	ds_read_b128 v[88:91], v70
	ds_read_b128 v[200:203], v74
	ds_read_b128 v[166:169], v96 offset:2304
	ds_read_b128 v[170:173], v96 offset:2368
	ds_read_b128 v[98:101], v71
	ds_read_b128 v[102:105], v75
	ds_read_b128 v[106:109], v72
	ds_read_b128 v[110:113], v76
	s_waitcnt lgkmcnt(9)
	v_mfma_f32_16x16x32_bf16 v[80:83], v[148:151], v[26:29], v[80:83]
	v_mfma_f32_16x16x32_bf16 v[84:87], v[148:151], v[34:37], v[84:87]
	ds_read_b128 v[174:177], v96 offset:4608
	ds_read_b128 v[178:181], v96 offset:4672
	ds_read_b128 v[182:185], v96 offset:6912
	ds_read_b128 v[186:189], v96 offset:6976
	s_waitcnt lgkmcnt(12)
	v_mfma_f32_16x16x32_bf16 v[80:83], v[152:155], v[30:33], v[80:83]
	v_mfma_f32_16x16x32_bf16 v[84:87], v[152:155], v[38:41], v[84:87]
	s_waitcnt lgkmcnt(9)
	v_mfma_f32_16x16x32_bf16 v[88:91], v[166:169], v[26:29], v[88:91]
	v_mfma_f32_16x16x32_bf16 v[200:203], v[166:169], v[34:37], v[200:203]
	s_waitcnt lgkmcnt(8)
	v_mfma_f32_16x16x32_bf16 v[88:91], v[170:173], v[30:33], v[88:91]
	v_mfma_f32_16x16x32_bf16 v[200:203], v[170:173], v[38:41], v[200:203]
	s_waitcnt lgkmcnt(3)
	v_mfma_f32_16x16x32_bf16 v[98:101], v[174:177], v[26:29], v[98:101]
	v_mfma_f32_16x16x32_bf16 v[102:105], v[174:177], v[34:37], v[102:105]
	s_waitcnt lgkmcnt(2)
	v_mfma_f32_16x16x32_bf16 v[98:101], v[178:181], v[30:33], v[98:101]
	v_mfma_f32_16x16x32_bf16 v[102:105], v[178:181], v[38:41], v[102:105]
	s_waitcnt lgkmcnt(1)
	v_mfma_f32_16x16x32_bf16 v[106:109], v[182:185], v[26:29], v[106:109]
	v_mfma_f32_16x16x32_bf16 v[110:113], v[182:185], v[34:37], v[110:113]
	s_waitcnt lgkmcnt(0)
	v_mfma_f32_16x16x32_bf16 v[106:109], v[186:189], v[30:33], v[106:109]
	v_mfma_f32_16x16x32_bf16 v[110:113], v[186:189], v[38:41], v[110:113]
	s_add_i32 s0, s14, 1
	v_mov_b32_e32 v161, s0
	s_add_i32 s0, s15, 0xffffff00
	v_mov_b32_e32 v165, s0
	ds_read_u8 v97, v161
	ds_read_b32 v217, v165
	s_cmp_eq_u32 s1, 0
	s_cbranch_scc1 .Lmy_a_nonuni
	ds_read_b128 v[148:151], v96 offset:14336
	ds_read_b128 v[152:155], v96 offset:16640
	ds_read_b128 v[166:169], v96 offset:18944
	ds_read_b128 v[170:173], v96 offset:21248
	ds_read_b128 v[174:177], v96 offset:14400
	ds_read_b128 v[178:181], v96 offset:16704
	ds_read_b128 v[182:185], v96 offset:19008
	ds_read_b128 v[186:189], v96 offset:21312
.Lmy_a_exp:
	v_exp_f32_e32 v63, v80
	v_exp_f32_e32 v62, v84
	v_exp_f32_e32 v65, v81
	v_exp_f32_e32 v64, v85
	v_exp_f32_e32 v67, v82
	v_exp_f32_e32 v66, v86
	v_pk_add_f32 v[142:143], v[62:63], v[64:65]
	v_exp_f32_e32 v69, v83
	v_exp_f32_e32 v68, v87
	v_pk_add_f32 v[142:143], v[142:143], v[66:67]
	v_exp_f32_e32 v71, v88
	v_exp_f32_e32 v70, v200
	v_pk_add_f32 v[142:143], v[142:143], v[68:69]
	v_exp_f32_e32 v73, v89
	v_exp_f32_e32 v72, v201
	v_pk_add_f32 v[142:143], v[142:143], v[70:71]
	v_exp_f32_e32 v75, v90
	v_exp_f32_e32 v74, v202
	v_pk_add_f32 v[142:143], v[142:143], v[72:73]
	v_exp_f32_e32 v77, v91
	v_exp_f32_e32 v76, v203
	v_pk_add_f32 v[142:143], v[142:143], v[74:75]
	v_exp_f32_e32 v219, v98
	v_exp_f32_e32 v218, v102
	v_pk_add_f32 v[142:143], v[142:143], v[76:77]
	v_exp_f32_e32 v221, v99
	v_exp_f32_e32 v220, v103
	v_pk_add_f32 v[142:143], v[142:143], v[218:219]
	v_exp_f32_e32 v223, v100
	v_exp_f32_e32 v222, v104
	v_pk_add_f32 v[142:143], v[142:143], v[220:221]
	v_exp_f32_e32 v225, v101
	v_exp_f32_e32 v224, v105
	v_pk_add_f32 v[142:143], v[142:143], v[222:223]
	v_exp_f32_e32 v231, v106
	v_exp_f32_e32 v230, v110
	v_pk_add_f32 v[142:143], v[142:143], v[224:225]
	v_exp_f32_e32 v233, v107
	v_exp_f32_e32 v232, v111
	v_pk_add_f32 v[142:143], v[142:143], v[230:231]
	v_exp_f32_e32 v235, v108
	v_exp_f32_e32 v234, v112
	v_pk_add_f32 v[142:143], v[142:143], v[232:233]
	v_exp_f32_e32 v237, v109
	v_exp_f32_e32 v236, v113
	v_pk_add_f32 v[142:143], v[142:143], v[234:235]
	s_nop 0
	v_pk_add_f32 v[142:143], v[142:143], v[236:237]
	v_cvt_pk_bf16_f32 v80, v63, v65
	v_cvt_pk_bf16_f32 v81, v67, v69
	v_cvt_pk_bf16_f32 v82, v71, v73
	v_cvt_pk_bf16_f32 v83, v75, v77
	v_cvt_pk_bf16_f32 v84, v62, v64
	v_cvt_pk_bf16_f32 v85, v66, v68
	v_cvt_pk_bf16_f32 v86, v70, v72
	v_cvt_pk_bf16_f32 v87, v74, v76
	s_waitcnt lgkmcnt(7)
	v_mfma_f32_16x16x32_bf16 v[50:53], v[148:151], v[80:83], v[50:53]
	v_mfma_f32_16x16x32_bf16 v[14:17], v[148:151], v[84:87], v[14:17]
	s_waitcnt lgkmcnt(6)
	v_mfma_f32_16x16x32_bf16 v[42:45], v[152:155], v[80:83], v[42:45]
	v_mfma_f32_16x16x32_bf16 v[10:13], v[152:155], v[84:87], v[10:13]
	s_waitcnt lgkmcnt(5)
	v_mfma_f32_16x16x32_bf16 v[22:25], v[166:169], v[80:83], v[22:25]
	v_mfma_f32_16x16x32_bf16 v[6:9], v[166:169], v[84:87], v[6:9]
	v_cvt_pk_bf16_f32 v88, v219, v221
	v_cvt_pk_bf16_f32 v89, v223, v225
	v_cvt_pk_bf16_f32 v90, v231, v233
	s_waitcnt lgkmcnt(4)
	v_mfma_f32_16x16x32_bf16 v[18:21], v[170:173], v[80:83], v[18:21]
	v_cvt_pk_bf16_f32 v91, v235, v237
	v_mfma_f32_16x16x32_bf16 v[2:5], v[170:173], v[84:87], v[2:5]
	v_cvt_pk_bf16_f32 v200, v218, v220
	v_cvt_pk_bf16_f32 v201, v222, v224
	v_cvt_pk_bf16_f32 v202, v230, v232
	s_waitcnt lgkmcnt(3)
	v_mfma_f32_16x16x32_bf16 v[50:53], v[174:177], v[88:91], v[50:53]
	v_cvt_pk_bf16_f32 v203, v234, v236
	s_nop 1
	v_mfma_f32_16x16x32_bf16 v[14:17], v[174:177], v[200:203], v[14:17]
	s_waitcnt lgkmcnt(2)
	v_mfma_f32_16x16x32_bf16 v[42:45], v[178:181], v[88:91], v[42:45]
	v_mfma_f32_16x16x32_bf16 v[10:13], v[178:181], v[200:203], v[10:13]
	s_waitcnt lgkmcnt(1)
	v_mfma_f32_16x16x32_bf16 v[22:25], v[182:185], v[88:91], v[22:25]
	v_mfma_f32_16x16x32_bf16 v[6:9], v[182:185], v[200:203], v[6:9]
	s_waitcnt lgkmcnt(0)
	v_mfma_f32_16x16x32_bf16 v[18:21], v[186:189], v[88:91], v[18:21]
	v_mfma_f32_16x16x32_bf16 v[2:5], v[186:189], v[200:203], v[2:5]
	s_branch .LBB0_341

; #define LAS __attribute__((address_space(3)))
; template <int DQK, int MODE>
; __device__ __forceinline__ void attn_unit(LAS unsigned char* lds, const AttnArgs& a, const unsigned char* lut) {
;     ...
;     for (int kt = kt_lo; kt <= kt_hi; ++kt) {
;         const int cur = (kt - kt_lo) & 1;
;         if (kt < kt_hi) ATT_STORE(cur ^ 1);
;         if (kt + 1 < kt_hi) ATT_LOAD(kt + 2);
;         const unsigned long long mwc0 = mwn0, mwc1 = mwn1;
;         if (MODE == 2 && kt < kt_hi) { mwn0 = a.mask[(long)qi * 128 + kt + 1]; mwn1 = a.mask[(long)(qi + 16) * 128 + kt + 1]; }
;         const LAS bf16_t* sK = (const LAS bf16_t*)(lds + cur * 24576); const LAS bf16_t* sVt = (const LAS bf16_t*)(lds + cur * 24576 + 14336);
;         const int key0 = kt * 64;
;         bool skip = key0 > wq_max;
;         if (MODE == 1) skip = skip || (key0 + 63 < wq_min - a.maxdist);
;         if (!skip) {
;             unsigned mlo[2] = {0u, 0u}, mhi[2] = {0u, 0u};
;             if (MODE == 0) {
;                 if (key0 + 63 <= wq_min) attn_tile<DQK, 0>(sK, sVt, sBias, qf, o, lsum, qi, key0, 0, mlo, mhi, nb, lr, lg);
;                 else attn_tile<DQK, 1>(sK, sVt, sBias, qf, o, lsum, qi, key0, 0, mlo, mhi, nb, lr, lg);
;             } else if (MODE == 1) {
;                 attn_tile<DQK, 2>(sK, sVt, sBias, qf, o, lsum, qi, key0, a.maxdist, mlo, mhi, nb, lr, lg);
;             } else {
;                 const unsigned long long w0 = mwc0 >> (lg * 4), w1 = mwc1 >> (lg * 4);
;                 mlo[0] = (unsigned)w0; mhi[0] = (unsigned)(w0 >> 32); mlo[1] = (unsigned)w1; mhi[1] = (unsigned)(w1 >> 32);
;                 const int uni = __builtin_amdgcn_readfirstlane((int)sUni[wid * 132 + kt]);
;                 if (uni) { const float ub = sBias[96 + wq_min - key0]; attn_tile<DQK, 3>(sK, sVt, sBias, qf, o, lsum, qi, key0, 0, mlo, mhi, nb + ub, lr, lg); }
;                 else attn_tile<DQK, 4>(sK, sVt, sBias, qf, o, lsum, qi, key0, 0, mlo, mhi, nb, lr, lg);
;             }
;         }
;         __syncthreads();
;     }
.LBB0_341:
	v_pk_add_f32 v[94:95], v[94:95], v[142:143]
.LBB0_342:
	s_add_i32 s14, s14, 1
	s_add_i32 s16, s16, 64
	s_addk_i32 s15, 0xff00
	v_lshl_add_u64 v[128:129], v[128:129], 0, 8
	v_lshl_add_u64 v[130:131], v[130:131], 0, 8
	v_lshl_add_u64 v[132:133], v[132:133], 0, s[26:27]
	v_lshl_add_u64 v[134:135], v[134:135], 0, s[26:27]
	s_cmp_eq_u32 s17, s12
	v_add_u32_e32 v123, 0xffffff00, v123
	s_waitcnt lgkmcnt(0)
	s_barrier
	s_cbranch_scc1 .LBB0_310
	s_waitcnt vmcnt(3)
	v_mov_b64_e32 v[62:63], v[140:141]
	v_mov_b64_e32 v[64:65], v[138:139]
	s_mov_b32 s17, s18
	s_branch .LBB0_331

; #define ATT_LOAD(kt) do { const long kb_ = (long)(kt) * 64; \
;         rk0 = *(const u32x4*)(a.k + (kb_ + kkey0) * a.k_rs + kpart0 * 8); \
;         if (DQK == 96 && tid < 256) rk1 = *(const u32x4*)(a.k + (kb_ + kkey1) * a.k_rs + kpart1 * 8); \
;         rv0 = *(const u32x2*)(a.v + (kb_ + 2 * vkp) * a.v_rs + vdg * 4); rv1 = *(const u32x2*)(a.v + (kb_ + 2 * vkp + 1) * a.v_rs + vdg * 4); } while (0)
; template <int DQK, int MODE>
; __device__ __forceinline__ void attn_unit(LAS unsigned char* lds, const AttnArgs& a, const unsigned char* lut) {
;     ...
;     float lsum[2]; lsum[0] = (lg == 0) ? a.l_init : 0.f; lsum[1] = lsum[0];
;     const float nb = -a.bound;
;     f32x4 o[2][4];
; #pragma unroll
;     for (int qt = 0; qt < 2; ++qt)
; #pragma unroll
;         for (int d = 0; d < 4; ++d) o[qt][d] = (f32x4){0.f, 0.f, 0.f, 0.f};
;     u32x4 rk0, rk1; u32x2 rv0, rv1;
;     const int kkey0 = tid / KCH, kpart0 = tid % KCH; const int kkey1 = (tid + 512) / KCH, kpart1 = (tid + 512) % KCH;
;     const int vkp = tid & 31, vdg = tid >> 5;
;     ...
;     ATT_LOAD(kt_lo);
;     ATT_STORE(0);
;     if (kt_lo < kt_hi) ATT_LOAD(kt_lo + 1);
;     unsigned long long mwn0 = 0ull, mwn1 = 0ull;
;     if (MODE == 2) { mwn0 = a.mask[(long)qi * 128 + kt_lo]; mwn1 = a.mask[(long)(qi + 16) * 128 + kt_lo]; }
;     __syncthreads();
.LBB0_366:
	v_cmp_eq_u32_e64 s[36:37], 0, v10
	s_mov_b64 s[54:55], -1
	s_cmp_le_i32 s13, s14
	v_cndmask_b32_e64 v120, 0, v0, s[36:37]
	v_lshlrev_b32_e32 v166, 2, v10
	s_waitcnt lgkmcnt(0)
	s_barrier
	s_cbranch_scc0 .LBB0_376
	s_lshl_b32 s1, s17, 1
	s_or_b32 s15, s18, 31
	s_sub_i32 s16, s18, s16
	s_and_b32 s1, s1, 0xffffff80
	s_add_u32 s1, s1, 0x102
	v_and_b32_e32 v5, 31, v8
	s_addc_u32 s17, 0, 0
	v_lshl_or_b32 v5, v5, 2, s1
	v_mad_u64_u32 v[8:9], s[20:21], s52, v5, v[6:7]
	v_mov_b32_e32 v5, s17
	s_lshl_b32 s17, s52, 7
	s_add_u32 s0, s0, 0x80
	v_mad_u32_u24 v9, s52, v5, v9
	v_or_b32_e32 v5, s0, v11
	s_addc_u32 s1, 0, 0
	v_mad_u64_u32 v[6:7], s[20:21], s76, v5, v[6:7]
	v_lshl_add_u64 v[124:125], s[56:57], 0, v[6:7]
	v_lshl_add_u64 v[2:3], s[0:1], 0, v[2:3]
	v_lshlrev_b64 v[6:7], 1, v[114:115]
	v_lshlrev_b32_e32 v0, 2, v10
	v_mad_u64_u32 v[6:7], s[0:1], s76, v2, v[6:7]
	v_add_u32_e32 v2, s18, v4
	v_sub_u32_e32 v2, v2, v0
	s_lshl_b32 s18, s13, 6
	v_subrev_u32_e32 v2, s18, v2
	v_readlane_b32 s0, v254, 33
	v_xor_b32_e32 v54, 0x80000000, v110
	v_mov_b32_e32 v121, v120
	v_mad_i32_i24 v7, s76, v3, v7
	v_lshl_add_u32 v115, v2, 2, s0
	v_mov_b32_e32 v2, 0
	v_lshlrev_b32_e32 v167, 3, v10
	v_mov_b32_e32 v55, v54
	v_mov_b32_e32 v56, v54
	v_mov_b32_e32 v57, v54
	v_mul_u32_u24_e32 v168, 0x90, v4
	v_and_b32_e32 v214, 3, v4
	v_mul_u32_u24_e32 v214, 0x544, v214
	v_add_u32_e32 v214, 0x223f4, v214
	v_readfirstlane_b32 s0, v192
	s_bitcmp1_b32 s0, 8
	s_cbranch_scc0 .Lmy_prio_bd
	s_setprio 1
.Lmy_prio_bd:
	v_lshl_add_u64 v[122:123], s[56:57], 0, v[8:9]
	v_lshl_add_u64 v[126:127], s[38:39], 0, v[6:7]
	s_mov_b64 s[0:1], 0
	s_mov_b32 s19, 0
	v_mov_b64_e32 v[128:129], v[120:121]
	v_mov_b32_e32 v3, v2
	v_mov_b32_e32 v4, v2
	v_mov_b32_e32 v5, v2
	v_mov_b32_e32 v6, v2
	v_mov_b32_e32 v7, v2
	v_mov_b32_e32 v8, v2
	v_mov_b32_e32 v9, v2
	v_mov_b32_e32 v10, v2
	v_mov_b32_e32 v11, v2
	v_mov_b32_e32 v12, v2
	v_mov_b32_e32 v13, v2
	v_mov_b32_e32 v14, v2
	v_mov_b32_e32 v15, v2
	v_mov_b32_e32 v16, v2
	v_mov_b32_e32 v17, v2
	v_mov_b32_e32 v18, v2
	v_mov_b32_e32 v19, v2
	v_mov_b32_e32 v20, v2
	v_mov_b32_e32 v21, v2
	v_mov_b32_e32 v22, v2
	v_mov_b32_e32 v23, v2
	v_mov_b32_e32 v24, v2
	v_mov_b32_e32 v25, v2
	v_mov_b32_e32 v46, v2
	v_mov_b32_e32 v47, v2
	v_mov_b32_e32 v48, v2
	v_mov_b32_e32 v49, v2
	v_mov_b32_e32 v50, v2
	v_mov_b32_e32 v51, v2
	v_mov_b32_e32 v52, v2
	v_mov_b32_e32 v53, v2
	v_mov_b32_e32 v59, v120
	v_mov_b32_e32 v58, v120
	s_branch .LBB0_369

; template <int DQK, int VAR> ...
;     ...
;         for (int c = 0; c < 2; ++c) {
;             s[0][ch * 2 + c] = (f32x4){sinit, sinit, sinit, sinit}; s[1][ch * 2 + c] = s[0][ch * 2 + c];
; #pragma unroll
;             for (int ks = 0; ks < DQK / 32; ++ks) {
;                 s[0][ch * 2 + c] = __builtin_amdgcn_mfma_f32_16x16x32_bf16(kfr[c][ks], qf[0][ks], s[0][ch * 2 + c], 0, 0, 0);
;                 s[1][ch * 2 + c] = __builtin_amdgcn_mfma_f32_16x16x32_bf16(kfr[c][ks], qf[1][ks], s[1][ch * 2 + c], 0, 0, 0);
;             }
;         }
;         __builtin_amdgcn_s_setprio(0);
;         __builtin_amdgcn_sched_barrier(0);
;     }
;     __builtin_amdgcn_s_setprio(0);
;     __builtin_amdgcn_sched_barrier(0);
; #pragma unroll
;     for (int kk = 0; kk < 2; ++kk)
; #pragma unroll
;         for (int dt = 0; dt < 4; ++dt) {
;             const LAS bf16_t* vp = sVt + (dt * 16 + lr) * VP + kk * 32 + lg * 4;
;             const u32x2 v0 = *(const LAS u32x2*)vp, v1 = *(const LAS u32x2*)(vp + 16);
;             vfr[kk][dt].x = v0.x; vfr[kk][dt].y = v0.y; vfr[kk][dt].z = v1.x; vfr[kk][dt].w = v1.y;
;         }
;     __builtin_amdgcn_sched_barrier(0);
; #pragma unroll
;     for (int qt = 0; qt < 2; ++qt) {
;         const int dq = qi + qt * 16 - key0 - lg * 4;
;         const LAS float* bp = sBias + (dq + 33);
;         float ps = 0.f;
; #pragma unroll
;         for (int c = 0; c < 4; ++c)
; #pragma unroll
;             for (int j = 0; j < 4; ++j) {
;                 float val = s[qt][c][j]; float pv;
;                 if (VAR == 0) pv = fexp2(val);
;                 else if (VAR == 1) { pv = fexp2(val); pv = (dq >= c * 16 + j) ? pv : 0.f; }
;                 else if (VAR == 2) { pv = fexp2(val + bp[63 - (c * 16 + j)]); }
;                 else if (VAR == 3) { pv = fexp2(val); pv = __uint_as_float(__float_as_uint(pv) & (unsigned)__builtin_amdgcn_sbfe((int)(c < 2 ? mlo[qt] : mhi[qt]), (c & 1) * 16 + j, 1)); }
;                 else { pv = fexp2(val + bp[63 - (c * 16 + j)]); pv = __uint_as_float(__float_as_uint(pv) & (unsigned)__builtin_amdgcn_sbfe((int)(c < 2 ? mlo[qt] : mhi[qt]), (c & 1) * 16 + j, 1)); }
;                 s[qt][c][j] = pv; ps += pv;
;             }
;         lsum[qt] += ps;
;     }
;     __builtin_amdgcn_s_setprio(1);
; #pragma unroll
;     for (int kk = 0; kk < 2; ++kk) {
;         bf16x8 pb[2];
; #pragma unroll
;         for (int qt = 0; qt < 2; ++qt) {
.LBB0_373:
	s_cmp_gt_i32 s18, s15
	s_cselect_b64 s[22:23], -1, 0
	s_add_i32 s21, s18, 63
	s_cmp_lt_i32 s21, s16
	s_cselect_b64 s[38:39], -1, 0
	s_or_b64 s[22:23], s[22:23], s[38:39]
	s_and_b64 vcc, exec, s[22:23]
	s_cbranch_vccnz .LBB0_368
	s_mulk_i32 s20, 0x6000
	s_add_i32 s20, s20, 0
	v_add3_u32 v78, s20, v112, v168
	v_sub_u32_e32 v86, v214, v115
	ds_read_b128 v[180:183], v86 offset:64
	ds_read_b128 v[184:187], v86
	ds_read_b128 v[58:61], v78
	ds_read_b128 v[62:65], v78 offset:64
	ds_read_b128 v[188:191], v86 offset:128
	ds_read_b128 v[200:203], v86 offset:64
	ds_read_b128 v[66:69], v78 offset:2304
	ds_read_b128 v[70:73], v78 offset:2368
	ds_read_b128 v[218:221], v86 offset:192
	ds_read_b128 v[222:225], v86 offset:128
	ds_read_b128 v[230:233], v86 offset:256
	ds_read_b128 v[234:237], v86 offset:192
	s_waitcnt lgkmcnt(9)
	v_mfma_f32_16x16x32_bf16 v[180:183], v[58:61], v[26:29], v[180:183]
	v_mfma_f32_16x16x32_bf16 v[184:187], v[58:61], v[34:37], v[184:187]
	ds_read_b128 v[74:77], v78 offset:4608
	ds_read_b128 v[82:85], v78 offset:4672
	ds_read_b128 v[86:89], v78 offset:6912
	ds_read_b128 v[98:101], v78 offset:6976
	s_waitcnt lgkmcnt(12)
	v_mfma_f32_16x16x32_bf16 v[180:183], v[62:65], v[30:33], v[180:183]
	v_mfma_f32_16x16x32_bf16 v[184:187], v[62:65], v[38:41], v[184:187]
	s_waitcnt lgkmcnt(9)
	v_mfma_f32_16x16x32_bf16 v[188:191], v[66:69], v[26:29], v[188:191]
	v_mfma_f32_16x16x32_bf16 v[200:203], v[66:69], v[34:37], v[200:203]
	s_waitcnt lgkmcnt(8)
	v_mfma_f32_16x16x32_bf16 v[188:191], v[70:73], v[30:33], v[188:191]
	v_mfma_f32_16x16x32_bf16 v[200:203], v[70:73], v[38:41], v[200:203]
	s_waitcnt lgkmcnt(3)
	v_mfma_f32_16x16x32_bf16 v[218:221], v[74:77], v[26:29], v[218:221]
	v_mfma_f32_16x16x32_bf16 v[222:225], v[74:77], v[34:37], v[222:225]
	s_waitcnt lgkmcnt(2)
	v_mfma_f32_16x16x32_bf16 v[218:221], v[82:85], v[30:33], v[218:221]
	v_mfma_f32_16x16x32_bf16 v[222:225], v[82:85], v[38:41], v[222:225]
	s_waitcnt lgkmcnt(1)
	v_mfma_f32_16x16x32_bf16 v[230:233], v[86:89], v[26:29], v[230:233]
	v_mfma_f32_16x16x32_bf16 v[234:237], v[86:89], v[34:37], v[234:237]
	s_waitcnt lgkmcnt(0)
	v_mfma_f32_16x16x32_bf16 v[230:233], v[98:101], v[30:33], v[230:233]
	v_mfma_f32_16x16x32_bf16 v[234:237], v[98:101], v[38:41], v[234:237]
	v_mov_b32_e32 v86, v78
	ds_read_b128 v[58:61], v86 offset:14336
	ds_read_b128 v[66:69], v86 offset:16640
	ds_read_b128 v[74:77], v86 offset:18944
	ds_read_b128 v[82:85], v86 offset:21248
	ds_read_b128 v[62:65], v86 offset:14400
	ds_read_b128 v[70:73], v86 offset:16704
	ds_read_b128 v[78:81], v86 offset:19008
	ds_read_b128 v[86:89], v86 offset:21312
	v_exp_f32_e32 v130, v180
	v_exp_f32_e32 v131, v184
	v_exp_f32_e32 v132, v181
	v_exp_f32_e32 v133, v185
	v_exp_f32_e32 v134, v182
	v_exp_f32_e32 v135, v186
	v_pk_add_f32 v[90:91], v[130:131], v[132:133]
	v_exp_f32_e32 v136, v183
	v_exp_f32_e32 v137, v187
	v_pk_add_f32 v[90:91], v[90:91], v[134:135]
	v_exp_f32_e32 v138, v188
	v_exp_f32_e32 v139, v200
	v_pk_add_f32 v[90:91], v[90:91], v[136:137]
	v_exp_f32_e32 v140, v189
	v_exp_f32_e32 v141, v201
	v_pk_add_f32 v[90:91], v[90:91], v[138:139]
	v_exp_f32_e32 v142, v190
	v_exp_f32_e32 v143, v202
	v_pk_add_f32 v[90:91], v[90:91], v[140:141]
	v_exp_f32_e32 v144, v191
	v_exp_f32_e32 v145, v203
	v_pk_add_f32 v[90:91], v[90:91], v[142:143]
	v_exp_f32_e32 v146, v218
	v_exp_f32_e32 v147, v222
	v_pk_add_f32 v[90:91], v[90:91], v[144:145]
	v_exp_f32_e32 v148, v219
	v_exp_f32_e32 v149, v223
	v_pk_add_f32 v[90:91], v[90:91], v[146:147]
	v_exp_f32_e32 v150, v220
	v_exp_f32_e32 v151, v224
	v_pk_add_f32 v[90:91], v[90:91], v[148:149]
	v_exp_f32_e32 v152, v221
	v_exp_f32_e32 v153, v225
	v_pk_add_f32 v[90:91], v[90:91], v[150:151]
	v_exp_f32_e32 v154, v230
	v_exp_f32_e32 v155, v234
	v_pk_add_f32 v[90:91], v[90:91], v[152:153]
	v_exp_f32_e32 v156, v231
	v_exp_f32_e32 v157, v235
	v_pk_add_f32 v[90:91], v[90:91], v[154:155]
	v_exp_f32_e32 v158, v232
	v_exp_f32_e32 v159, v236
	v_pk_add_f32 v[90:91], v[90:91], v[156:157]
	v_exp_f32_e32 v160, v233
	v_exp_f32_e32 v161, v237
	v_pk_add_f32 v[90:91], v[90:91], v[158:159]
	s_nop 0
	v_pk_add_f32 v[90:91], v[90:91], v[160:161]
	s_nop 0
	v_pk_add_f32 v[128:129], v[128:129], v[90:91]
	v_cvt_pk_bf16_f32 v90, v130, v132
	v_cvt_pk_bf16_f32 v91, v134, v136
	v_cvt_pk_bf16_f32 v92, v138, v140
	v_cvt_pk_bf16_f32 v93, v142, v144
	v_cvt_pk_bf16_f32 v94, v131, v133
	v_cvt_pk_bf16_f32 v95, v135, v137
	v_cvt_pk_bf16_f32 v96, v139, v141
	v_cvt_pk_bf16_f32 v97, v143, v145
	s_waitcnt lgkmcnt(7)
	v_mfma_f32_16x16x32_bf16 v[50:53], v[58:61], v[90:93], v[50:53]
	v_mfma_f32_16x16x32_bf16 v[14:17], v[58:61], v[94:97], v[14:17]
	s_waitcnt lgkmcnt(6)
	v_mfma_f32_16x16x32_bf16 v[46:49], v[66:69], v[90:93], v[46:49]
	v_mfma_f32_16x16x32_bf16 v[10:13], v[66:69], v[94:97], v[10:13]
	v_cvt_pk_bf16_f32 v98, v146, v148
	v_cvt_pk_bf16_f32 v99, v150, v152
	v_cvt_pk_bf16_f32 v100, v154, v156
	v_cvt_pk_bf16_f32 v101, v158, v160
	s_waitcnt lgkmcnt(5)
	v_mfma_f32_16x16x32_bf16 v[22:25], v[74:77], v[90:93], v[22:25]
	v_mfma_f32_16x16x32_bf16 v[6:9], v[74:77], v[94:97], v[6:9]
	v_cvt_pk_bf16_f32 v102, v147, v149
	v_cvt_pk_bf16_f32 v103, v151, v153
	v_cvt_pk_bf16_f32 v104, v155, v157
	v_cvt_pk_bf16_f32 v105, v159, v161
	s_waitcnt lgkmcnt(4)
	v_mfma_f32_16x16x32_bf16 v[18:21], v[82:85], v[90:93], v[18:21]
	v_mfma_f32_16x16x32_bf16 v[2:5], v[82:85], v[94:97], v[2:5]
	s_waitcnt lgkmcnt(3)
	v_mfma_f32_16x16x32_bf16 v[50:53], v[62:65], v[98:101], v[50:53]
	v_mfma_f32_16x16x32_bf16 v[14:17], v[62:65], v[102:105], v[14:17]
	s_waitcnt lgkmcnt(2)
	v_mfma_f32_16x16x32_bf16 v[46:49], v[70:73], v[98:101], v[46:49]
	v_mfma_f32_16x16x32_bf16 v[10:13], v[70:73], v[102:105], v[10:13]
	s_waitcnt lgkmcnt(1)
	v_mfma_f32_16x16x32_bf16 v[22:25], v[78:81], v[98:101], v[22:25]
	v_mfma_f32_16x16x32_bf16 v[6:9], v[78:81], v[102:105], v[6:9]
	s_waitcnt lgkmcnt(0)
	v_mfma_f32_16x16x32_bf16 v[18:21], v[86:89], v[98:101], v[18:21]
	v_mfma_f32_16x16x32_bf16 v[2:5], v[86:89], v[102:105], v[2:5]
	v_mov_b32_e32 v59, v128
	v_mov_b32_e32 v58, v129
	s_branch .LBB0_368
.LBB0_375:
	s_setprio 0
	s_mov_b64 s[54:55], 0
